# de-serialized residual epilogues of OUT and FF2 res_tile: gate and x loads batched with two counted waits instead of 16 load-wait-store chains
# speedup vs baseline: 1.0149x; 1.0063x over previous
.LBB0_47:
	s_add_i32 s4, s16, 0xfffff000
	s_lshr_b32 s4, s4, 12
	s_add_i32 s4, s4, 1
	s_cmp_gt_i32 s17, 15
	s_cselect_b32 s4, s4, 0
	v_readlane_b32 s18, v254, 23
	s_add_u32 s4, s2, s4
	s_mul_hi_i32 s5, s18, 9
	s_addc_u32 s5, s5, 0
	s_waitcnt vmcnt(5)
	v_ashrrev_i32_e32 v66, 1, v134
	s_mulk_i32 s5, 0x6000
	s_mul_hi_u32 s17, s4, 0x6000
	v_and_b32_e32 v66, 0xffffffc0, v66
	s_add_i32 s17, s17, s5
	s_mulk_i32 s4, 0x6000
	v_add_u32_e32 v66, s16, v66
	s_add_u32 s4, s78, s4
	v_and_or_b32 v68, v134, 31, v66
	v_lshrrev_b32_e32 v66, 3, v134
	v_and_b32_e32 v0, 64, v134
	s_addc_u32 s5, s79, s17
	v_and_b32_e32 v66, 4, v66
	v_ashrrev_i32_e32 v69, 31, v68
	v_readlane_b32 s16, v254, 21
	v_or3_b32 v0, v0, v66, s15
	v_lshlrev_b64 v[66:67], 12, v[68:69]
	v_readlane_b32 s17, v254, 22
	s_add_u32 s4, s4, 0x1d485000
	v_lshlrev_b32_e32 v0, 2, v0
	v_lshl_add_u64 v[66:67], s[16:17], 0, v[66:67]
	s_addc_u32 s5, s5, 0
	s_waitcnt vmcnt(4)
	v_lshl_add_u64 v[70:71], v[66:67], 0, v[0:1]
	v_lshl_add_u64 v[66:67], s[4:5], 0, v[0:1]
	s_waitcnt vmcnt(3)
	v_readlane_b32 s19, v254, 24
	v_or_b32_e32 v122, 32, v68
	v_ashrrev_i32_e32 v123, 31, v122
	v_lshlrev_b64 v[122:123], 12, v[122:123]
	v_lshl_add_u64 v[122:123], s[16:17], 0, v[122:123]
	v_lshl_add_u64 v[122:123], v[122:123], 0, v[0:1]
	global_load_dwordx4 v[144:147], v[66:67], off
	global_load_dwordx4 v[148:151], v[66:67], off offset:32
	global_load_dwordx4 v[152:155], v[66:67], off offset:64
	global_load_dwordx4 v[156:159], v[66:67], off offset:96
	global_load_dwordx4 v[160:163], v[66:67], off offset:128
	global_load_dwordx4 v[164:167], v[66:67], off offset:160
	global_load_dwordx4 v[168:171], v[66:67], off offset:192
	global_load_dwordx4 v[172:175], v[66:67], off offset:224
	global_load_dwordx4 v[176:179], v[70:71], off
	global_load_dwordx4 v[180:183], v[70:71], off offset:32
	global_load_dwordx4 v[184:187], v[70:71], off offset:64
	global_load_dwordx4 v[188:191], v[70:71], off offset:96
	global_load_dwordx4 v[192:195], v[70:71], off offset:128
	global_load_dwordx4 v[196:199], v[70:71], off offset:160
	global_load_dwordx4 v[200:203], v[70:71], off offset:192
	global_load_dwordx4 v[204:207], v[70:71], off offset:224
	global_load_dwordx4 v[90:93], v[122:123], off
	global_load_dwordx4 v[94:97], v[122:123], off offset:32
	global_load_dwordx4 v[98:101], v[122:123], off offset:64
	global_load_dwordx4 v[102:105], v[122:123], off offset:96
	global_load_dwordx4 v[106:109], v[122:123], off offset:128
	global_load_dwordx4 v[110:113], v[122:123], off offset:160
	global_load_dwordx4 v[114:117], v[122:123], off offset:192
	global_load_dwordx4 v[118:121], v[122:123], off offset:224
	s_mov_b64 s[4:5], 0
	s_waitcnt vmcnt(8)
	v_pk_fma_f32 v[50:51], v[50:51], v[144:145], v[176:177]
	v_pk_fma_f32 v[52:53], v[52:53], v[146:147], v[178:179]
	v_pk_fma_f32 v[54:55], v[54:55], v[148:149], v[180:181]
	v_pk_fma_f32 v[56:57], v[56:57], v[150:151], v[182:183]
	v_pk_fma_f32 v[58:59], v[58:59], v[152:153], v[184:185]
	v_pk_fma_f32 v[60:61], v[60:61], v[154:155], v[186:187]
	v_pk_fma_f32 v[62:63], v[62:63], v[156:157], v[188:189]
	v_pk_fma_f32 v[64:65], v[64:65], v[158:159], v[190:191]
	v_pk_fma_f32 v[34:35], v[34:35], v[160:161], v[192:193]
	v_pk_fma_f32 v[36:37], v[36:37], v[162:163], v[194:195]
	v_pk_fma_f32 v[38:39], v[38:39], v[164:165], v[196:197]
	v_pk_fma_f32 v[40:41], v[40:41], v[166:167], v[198:199]
	v_pk_fma_f32 v[42:43], v[42:43], v[168:169], v[200:201]
	v_pk_fma_f32 v[44:45], v[44:45], v[170:171], v[202:203]
	v_pk_fma_f32 v[46:47], v[46:47], v[172:173], v[204:205]
	v_pk_fma_f32 v[48:49], v[48:49], v[174:175], v[206:207]
	global_store_dwordx4 v[70:71], v[50:53], off
	global_store_dwordx4 v[70:71], v[54:57], off offset:32
	global_store_dwordx4 v[70:71], v[58:61], off offset:64
	global_store_dwordx4 v[70:71], v[62:65], off offset:96
	global_store_dwordx4 v[70:71], v[34:37], off offset:128
	global_store_dwordx4 v[70:71], v[38:41], off offset:160
	global_store_dwordx4 v[70:71], v[42:45], off offset:192
	global_store_dwordx4 v[70:71], v[46:49], off offset:224
	s_waitcnt vmcnt(8)
	v_pk_fma_f32 v[18:19], v[18:19], v[144:145], v[90:91]
	v_pk_fma_f32 v[20:21], v[20:21], v[146:147], v[92:93]
	v_pk_fma_f32 v[22:23], v[22:23], v[148:149], v[94:95]
	v_pk_fma_f32 v[24:25], v[24:25], v[150:151], v[96:97]
	v_pk_fma_f32 v[26:27], v[26:27], v[152:153], v[98:99]
	v_pk_fma_f32 v[28:29], v[28:29], v[154:155], v[100:101]
	v_pk_fma_f32 v[30:31], v[30:31], v[156:157], v[102:103]
	v_pk_fma_f32 v[32:33], v[32:33], v[158:159], v[104:105]
	v_pk_fma_f32 v[2:3], v[2:3], v[160:161], v[106:107]
	v_pk_fma_f32 v[4:5], v[4:5], v[162:163], v[108:109]
	v_pk_fma_f32 v[6:7], v[6:7], v[164:165], v[110:111]
	v_pk_fma_f32 v[8:9], v[8:9], v[166:167], v[112:113]
	v_pk_fma_f32 v[10:11], v[10:11], v[168:169], v[114:115]
	v_pk_fma_f32 v[12:13], v[12:13], v[170:171], v[116:117]
	v_pk_fma_f32 v[14:15], v[14:15], v[172:173], v[118:119]
	v_pk_fma_f32 v[16:17], v[16:17], v[174:175], v[120:121]
	global_store_dwordx4 v[122:123], v[18:21], off
	global_store_dwordx4 v[122:123], v[22:25], off offset:32
	global_store_dwordx4 v[122:123], v[26:29], off offset:64
	global_store_dwordx4 v[122:123], v[30:33], off offset:96
	global_store_dwordx4 v[122:123], v[2:5], off offset:128
	global_store_dwordx4 v[122:123], v[6:9], off offset:160
	global_store_dwordx4 v[122:123], v[10:13], off offset:192
	global_store_dwordx4 v[122:123], v[14:17], off offset:224

.LBB0_108:
	s_add_i32 s7, s6, 0xfffff000
	s_waitcnt vmcnt(5)
	v_ashrrev_i32_e32 v66, 1, v134
	s_lshr_b32 s7, s7, 12
	v_and_b32_e32 v66, 0xffffffc0, v66
	s_add_i32 s7, s7, 1
	v_add_u32_e32 v66, s6, v66
	v_readlane_b32 s44, v253, 35
	s_cmp_gt_i32 s20, 15
	v_and_or_b32 v66, v134, 31, v66
	v_lshrrev_b32_e32 v67, 3, v134
	s_movk_i32 s6, 0x1000
	v_readlane_b32 s45, v253, 36
	v_readlane_b32 s46, v253, 37
	v_readlane_b32 s47, v253, 38
	v_readlane_b32 s20, v254, 21
	v_and_b32_e32 v0, 64, v134
	s_cselect_b32 s7, s7, 0
	v_readlane_b32 s8, v254, 23
	v_and_b32_e32 v67, 4, v67
	v_cmp_gt_i32_e32 vcc, s6, v66
	s_waitcnt vmcnt(1)
	v_mov_b32_e32 v82, s46
	v_mov_b32_e32 v83, s44
	v_mov_b32_e32 v84, s47
	v_mov_b32_e32 v85, s45
	v_readlane_b32 s21, v254, 22
	s_add_u32 s7, s2, s7
	s_mul_hi_i32 s8, s8, 9
	v_or3_b32 v0, v0, v67, s19
	v_cndmask_b32_e32 v67, v82, v83, vcc
	v_cndmask_b32_e32 v68, v84, v85, vcc
	s_waitcnt vmcnt(0)
	v_mov_b32_e32 v86, s21
	v_mov_b32_e32 v87, s20
	v_readlane_b32 s9, v254, 24
	s_addc_u32 s8, s8, 0
	v_cndmask_b32_e64 v69, v86, v68, s[0:1]
	v_cndmask_b32_e64 v68, v87, v67, s[0:1]
	v_add_u32_e32 v67, 0xfffff000, v66
	s_mulk_i32 s8, 0x6000
	s_mul_hi_u32 s9, s7, 0x6000
	v_cndmask_b32_e32 v67, v67, v66, vcc
	s_add_i32 s9, s9, s8
	s_mulk_i32 s7, 0x6000
	v_cndmask_b32_e64 v70, v66, v67, s[0:1]
	s_add_u32 s7, s78, s7
	v_ashrrev_i32_e32 v71, 31, v70
	s_addc_u32 s9, s79, s9
	v_lshlrev_b64 v[70:71], 12, v[70:71]
	s_add_u32 s8, s7, 0x1d482000
	v_lshl_add_u64 v[68:69], v[68:69], 0, v[70:71]
	v_lshlrev_b32_e32 v0, 2, v0
	s_addc_u32 s9, s9, 0
	v_lshl_add_u64 v[72:73], v[68:69], 0, v[0:1]
	v_lshl_add_u64 v[68:69], s[8:9], 0, v[0:1]
	v_ashrrev_i32_e32 v67, 31, v66
	v_lshlrev_b64 v[70:71], 12, v[66:67]
	v_lshl_add_u64 v[70:71], s[20:21], 0, v[70:71]
	v_lshl_add_u64 v[70:71], v[70:71], 0, v[0:1]
	v_readlane_b32 s48, v253, 39
	v_readlane_b32 s49, v253, 40
	v_readlane_b32 s50, v253, 41
	v_readlane_b32 s51, v253, 42
	v_readlane_b32 s52, v253, 43
	v_readlane_b32 s53, v253, 44
	v_readlane_b32 s54, v253, 45
	v_readlane_b32 s55, v253, 46
	v_readlane_b32 s56, v253, 47
	v_readlane_b32 s57, v253, 48
	v_readlane_b32 s58, v253, 49
	v_readlane_b32 s59, v253, 50
	v_or_b32_e32 v122, 32, v66
	v_cmp_gt_i32_e32 vcc, s6, v122
	s_nop 1
	v_cndmask_b32_e32 v123, v82, v83, vcc
	v_cndmask_b32_e32 v124, v84, v85, vcc
	v_cndmask_b32_e64 v125, v86, v124, s[0:1]
	v_cndmask_b32_e64 v124, v87, v123, s[0:1]
	v_add_u32_e32 v123, 0xfffff020, v66
	v_cndmask_b32_e32 v123, v123, v122, vcc
	v_cndmask_b32_e64 v126, v122, v123, s[0:1]
	v_ashrrev_i32_e32 v127, 31, v126
	v_lshlrev_b64 v[126:127], 12, v[126:127]
	v_ashrrev_i32_e32 v123, 31, v122
	v_lshl_add_u64 v[124:125], v[124:125], 0, v[126:127]
	v_lshlrev_b64 v[122:123], 12, v[122:123]
	v_lshl_add_u64 v[122:123], s[20:21], 0, v[122:123]
	v_lshl_add_u64 v[128:129], v[124:125], 0, v[0:1]
	v_lshl_add_u64 v[130:131], v[122:123], 0, v[0:1]
	global_load_dwordx4 v[144:147], v[68:69], off
	global_load_dwordx4 v[148:151], v[68:69], off offset:32
	global_load_dwordx4 v[152:155], v[68:69], off offset:64
	global_load_dwordx4 v[156:159], v[68:69], off offset:96
	global_load_dwordx4 v[160:163], v[68:69], off offset:128
	global_load_dwordx4 v[164:167], v[68:69], off offset:160
	global_load_dwordx4 v[168:171], v[68:69], off offset:192
	global_load_dwordx4 v[172:175], v[68:69], off offset:224
	global_load_dwordx4 v[176:179], v[72:73], off
	global_load_dwordx4 v[180:183], v[72:73], off offset:32
	global_load_dwordx4 v[184:187], v[72:73], off offset:64
	global_load_dwordx4 v[188:191], v[72:73], off offset:96
	global_load_dwordx4 v[192:195], v[72:73], off offset:128
	global_load_dwordx4 v[196:199], v[72:73], off offset:160
	global_load_dwordx4 v[200:203], v[72:73], off offset:192
	global_load_dwordx4 v[204:207], v[72:73], off offset:224
	global_load_dwordx4 v[90:93], v[128:129], off
	global_load_dwordx4 v[94:97], v[128:129], off offset:32
	global_load_dwordx4 v[98:101], v[128:129], off offset:64
	global_load_dwordx4 v[102:105], v[128:129], off offset:96
	global_load_dwordx4 v[106:109], v[128:129], off offset:128
	global_load_dwordx4 v[110:113], v[128:129], off offset:160
	global_load_dwordx4 v[114:117], v[128:129], off offset:192
	global_load_dwordx4 v[118:121], v[128:129], off offset:224
	s_mov_b64 s[6:7], 0
	s_waitcnt vmcnt(8) lgkmcnt(0)
	v_pk_fma_f32 v[50:51], v[50:51], v[144:145], v[176:177]
	v_pk_fma_f32 v[52:53], v[52:53], v[146:147], v[178:179]
	v_pk_fma_f32 v[54:55], v[54:55], v[148:149], v[180:181]
	v_pk_fma_f32 v[56:57], v[56:57], v[150:151], v[182:183]
	v_pk_fma_f32 v[58:59], v[58:59], v[152:153], v[184:185]
	v_pk_fma_f32 v[60:61], v[60:61], v[154:155], v[186:187]
	v_pk_fma_f32 v[62:63], v[62:63], v[156:157], v[188:189]
	v_pk_fma_f32 v[64:65], v[64:65], v[158:159], v[190:191]
	v_pk_fma_f32 v[34:35], v[34:35], v[160:161], v[192:193]
	v_pk_fma_f32 v[36:37], v[36:37], v[162:163], v[194:195]
	v_pk_fma_f32 v[38:39], v[38:39], v[164:165], v[196:197]
	v_pk_fma_f32 v[40:41], v[40:41], v[166:167], v[198:199]
	v_pk_fma_f32 v[42:43], v[42:43], v[168:169], v[200:201]
	v_pk_fma_f32 v[44:45], v[44:45], v[170:171], v[202:203]
	v_pk_fma_f32 v[46:47], v[46:47], v[172:173], v[204:205]
	v_pk_fma_f32 v[48:49], v[48:49], v[174:175], v[206:207]
	global_store_dwordx4 v[70:71], v[50:53], off
	global_store_dwordx4 v[70:71], v[54:57], off offset:32
	global_store_dwordx4 v[70:71], v[58:61], off offset:64
	global_store_dwordx4 v[70:71], v[62:65], off offset:96
	global_store_dwordx4 v[70:71], v[34:37], off offset:128
	global_store_dwordx4 v[70:71], v[38:41], off offset:160
	global_store_dwordx4 v[70:71], v[42:45], off offset:192
	global_store_dwordx4 v[70:71], v[46:49], off offset:224
	s_waitcnt vmcnt(8)
	v_pk_fma_f32 v[18:19], v[18:19], v[144:145], v[90:91]
	v_pk_fma_f32 v[20:21], v[20:21], v[146:147], v[92:93]
	v_pk_fma_f32 v[22:23], v[22:23], v[148:149], v[94:95]
	v_pk_fma_f32 v[24:25], v[24:25], v[150:151], v[96:97]
	v_pk_fma_f32 v[26:27], v[26:27], v[152:153], v[98:99]
	v_pk_fma_f32 v[28:29], v[28:29], v[154:155], v[100:101]
	v_pk_fma_f32 v[30:31], v[30:31], v[156:157], v[102:103]
	v_pk_fma_f32 v[32:33], v[32:33], v[158:159], v[104:105]
	v_pk_fma_f32 v[2:3], v[2:3], v[160:161], v[106:107]
	v_pk_fma_f32 v[4:5], v[4:5], v[162:163], v[108:109]
	v_pk_fma_f32 v[6:7], v[6:7], v[164:165], v[110:111]
	v_pk_fma_f32 v[8:9], v[8:9], v[166:167], v[112:113]
	v_pk_fma_f32 v[10:11], v[10:11], v[168:169], v[114:115]
	v_pk_fma_f32 v[12:13], v[12:13], v[170:171], v[116:117]
	v_pk_fma_f32 v[14:15], v[14:15], v[172:173], v[118:119]
	v_pk_fma_f32 v[16:17], v[16:17], v[174:175], v[120:121]
	global_store_dwordx4 v[130:131], v[18:21], off
	global_store_dwordx4 v[130:131], v[22:25], off offset:32
	global_store_dwordx4 v[130:131], v[26:29], off offset:64
	global_store_dwordx4 v[130:131], v[30:33], off offset:96
	global_store_dwordx4 v[130:131], v[2:5], off offset:128
	global_store_dwordx4 v[130:131], v[6:9], off offset:160
	global_store_dwordx4 v[130:131], v[10:13], off offset:192
	global_store_dwordx4 v[130:131], v[14:17], off offset:224
